# proj-L0 GEMM k-loop hand-rescheduled: next-tile global loads issued at loop top, pipelined LDS fragment reads with counted lgkmcnt
# speedup vs baseline: 1.0053x; 1.0053x over previous
.LBB0_354:
	s_mov_b32 s98, 0x80
	s_mov_b32 s99, 0
	v_add3_u32 v209, v208, v164, 16
	v_add3_u32 v221, v207, v164, 16
.Lgk_p0:
	s_and_b32 s19, s8, 0x10000
	s_add_i32 s8, s8, 0x10000
	global_load_dwordx4 v[128:131], v[176:177], off
	global_load_dwordx4 v[132:135], v[184:185], off
	global_load_dwordx4 v[136:139], v[178:179], off
	global_load_dwordx4 v[140:143], v[186:187], off
	global_load_dwordx4 v[144:147], v[180:181], off
	global_load_dwordx4 v[148:151], v[188:189], off
	global_load_dwordx4 v[152:155], v[182:183], off
	global_load_dwordx4 v[156:159], v[190:191], off
	v_add3_u32 v227, v206, v221, s19
	v_add3_u32 v226, v206, v209, s19
	ds_read_b128 v[248:251], v227 offset:32768
	ds_read_b128 v[160:163], v227 offset:36864
	ds_read_b128 v[228:231], v226
	ds_read_b128 v[232:235], v226 offset:4096
	ds_read_b128 v[236:239], v226 offset:8192
	ds_read_b128 v[240:243], v226 offset:12288
	v_add3_u32 v226, v205, v209, s19
	ds_read_b128 v[244:247], v226
	v_lshl_add_u64 v[176:177], v[176:177], 0, s[98:99]
	v_lshl_add_u64 v[184:185], v[184:185], 0, s[98:99]
	v_lshl_add_u64 v[178:179], v[178:179], 0, s[98:99]
	v_lshl_add_u64 v[186:187], v[186:187], 0, s[98:99]
	v_lshl_add_u64 v[180:181], v[180:181], 0, s[98:99]
	v_lshl_add_u64 v[188:189], v[188:189], 0, s[98:99]
	v_lshl_add_u64 v[182:183], v[182:183], 0, s[98:99]
	v_lshl_add_u64 v[190:191], v[190:191], 0, s[98:99]
	v_add3_u32 v227, v205, v221, s19
	ds_read_b128 v[210:213], v227 offset:32768
	ds_read_b128 v[222:225], v227 offset:36864
	s_waitcnt lgkmcnt(6)
	v_mfma_f32_32x32x16_bf16 v[112:127], v[228:231], v[248:251], v[112:127]
	v_mfma_f32_32x32x16_bf16 v[96:111], v[228:231], v[160:163], v[96:111]
	ds_read_b128 v[228:231], v226 offset:4096
	s_waitcnt lgkmcnt(6)
	v_mfma_f32_32x32x16_bf16 v[80:95], v[232:235], v[248:251], v[80:95]
	v_mfma_f32_32x32x16_bf16 v[64:79], v[232:235], v[160:163], v[64:79]
	ds_read_b128 v[232:235], v226 offset:8192
	s_waitcnt lgkmcnt(6)
	v_mfma_f32_32x32x16_bf16 v[48:63], v[236:239], v[248:251], v[48:63]
	v_mfma_f32_32x32x16_bf16 v[32:47], v[236:239], v[160:163], v[32:47]
	ds_read_b128 v[236:239], v226 offset:12288
	s_waitcnt lgkmcnt(6)
	v_mfma_f32_32x32x16_bf16 v[16:31], v[240:243], v[248:251], v[16:31]
	v_mfma_f32_32x32x16_bf16 v[0:15], v[240:243], v[160:163], v[0:15]
	v_add3_u32 v226, v204, v209, s19
	ds_read_b128 v[240:243], v226
	v_add3_u32 v227, v204, v221, s19
	ds_read_b128 v[248:251], v227 offset:32768
	ds_read_b128 v[160:163], v227 offset:36864
	s_waitcnt lgkmcnt(6)
	v_mfma_f32_32x32x16_bf16 v[112:127], v[244:247], v[210:213], v[112:127]
	v_mfma_f32_32x32x16_bf16 v[96:111], v[244:247], v[222:225], v[96:111]
	ds_read_b128 v[244:247], v226 offset:4096
	s_waitcnt lgkmcnt(6)
	v_mfma_f32_32x32x16_bf16 v[80:95], v[228:231], v[210:213], v[80:95]
	v_mfma_f32_32x32x16_bf16 v[64:79], v[228:231], v[222:225], v[64:79]
	ds_read_b128 v[228:231], v226 offset:8192
	s_waitcnt lgkmcnt(6)
	v_mfma_f32_32x32x16_bf16 v[48:63], v[232:235], v[210:213], v[48:63]
	v_mfma_f32_32x32x16_bf16 v[32:47], v[232:235], v[222:225], v[32:47]
	ds_read_b128 v[232:235], v226 offset:12288
	s_waitcnt lgkmcnt(6)
	v_mfma_f32_32x32x16_bf16 v[16:31], v[236:239], v[210:213], v[16:31]
	v_mfma_f32_32x32x16_bf16 v[0:15], v[236:239], v[222:225], v[0:15]
	v_add3_u32 v226, v203, v209, s19
	ds_read_b128 v[236:239], v226
	v_add3_u32 v227, v203, v221, s19
	ds_read_b128 v[210:213], v227 offset:32768
	ds_read_b128 v[222:225], v227 offset:36864
	s_waitcnt lgkmcnt(6)
	v_mfma_f32_32x32x16_bf16 v[112:127], v[240:243], v[248:251], v[112:127]
	v_mfma_f32_32x32x16_bf16 v[96:111], v[240:243], v[160:163], v[96:111]
	ds_read_b128 v[240:243], v226 offset:4096
	s_waitcnt lgkmcnt(6)
	v_mfma_f32_32x32x16_bf16 v[80:95], v[244:247], v[248:251], v[80:95]
	v_mfma_f32_32x32x16_bf16 v[64:79], v[244:247], v[160:163], v[64:79]
	ds_read_b128 v[244:247], v226 offset:8192
	s_waitcnt lgkmcnt(6)
	v_mfma_f32_32x32x16_bf16 v[48:63], v[228:231], v[248:251], v[48:63]
	v_mfma_f32_32x32x16_bf16 v[32:47], v[228:231], v[160:163], v[32:47]
	ds_read_b128 v[228:231], v226 offset:12288
	s_waitcnt lgkmcnt(6)
	v_mfma_f32_32x32x16_bf16 v[16:31], v[232:235], v[248:251], v[16:31]
	v_mfma_f32_32x32x16_bf16 v[0:15], v[232:235], v[160:163], v[0:15]
	s_xor_b32 s19, s19, 0x10000
	v_add3_u32 v253, v195, s19, 16
	s_waitcnt lgkmcnt(3)
	v_mfma_f32_32x32x16_bf16 v[112:127], v[236:239], v[210:213], v[112:127]
	v_mfma_f32_32x32x16_bf16 v[96:111], v[236:239], v[222:225], v[96:111]
	s_waitcnt vmcnt(6)
	ds_write_b128 v253, v[128:131]
	ds_write_b128 v253, v[132:135] offset:32768
	s_waitcnt lgkmcnt(4)
	v_mfma_f32_32x32x16_bf16 v[80:95], v[240:243], v[210:213], v[80:95]
	v_mfma_f32_32x32x16_bf16 v[64:79], v[240:243], v[222:225], v[64:79]
	s_waitcnt vmcnt(4)
	ds_write_b128 v253, v[136:139] offset:8192
	ds_write_b128 v253, v[140:143] offset:40960
	s_waitcnt lgkmcnt(5)
	v_mfma_f32_32x32x16_bf16 v[48:63], v[244:247], v[210:213], v[48:63]
	v_mfma_f32_32x32x16_bf16 v[32:47], v[244:247], v[222:225], v[32:47]
	s_waitcnt vmcnt(2)
	ds_write_b128 v253, v[144:147] offset:16384
	ds_write_b128 v253, v[148:151] offset:49152
	s_waitcnt lgkmcnt(6)
	v_mfma_f32_32x32x16_bf16 v[16:31], v[228:231], v[210:213], v[16:31]
	v_mfma_f32_32x32x16_bf16 v[0:15], v[228:231], v[222:225], v[0:15]
	s_waitcnt vmcnt(0)
	ds_write_b128 v253, v[152:155] offset:24576
	ds_write_b128 v253, v[156:159] offset:57344
	s_add_u32 s16, s16, 0x80
	s_waitcnt lgkmcnt(0)
	s_barrier
	s_cmpk_eq_i32 s16, 0x780
	s_cbranch_scc0 .Lgk_p0
	s_add_i32 s19, s66, s92
	s_cmpk_lt_i32 s19, 0x500
	s_cselect_b64 s[16:17], -1, 0
	s_add_i32 s8, 16, 0x10000
	v_add_u32_e32 v160, s8, v206
	v_add3_u32 v184, v160, v208, v164
	ds_read_b128 v[160:163], v184
	v_add_u32_e32 v176, s29, v206
	v_add3_u32 v180, v176, v207, v164
	ds_read_b128 v[176:179], v180
	ds_read_b128 v[180:183], v180 offset:4096
	s_and_b64 vcc, exec, s[16:17]
	s_waitcnt lgkmcnt(1)
	v_mfma_f32_32x32x16_bf16 v[112:127], v[160:163], v[176:179], v[112:127]
	s_waitcnt lgkmcnt(0)
	v_mfma_f32_32x32x16_bf16 v[96:111], v[160:163], v[180:183], v[96:111]
	ds_read_b128 v[160:163], v184 offset:4096
	s_waitcnt lgkmcnt(0)
	v_mfma_f32_32x32x16_bf16 v[80:95], v[160:163], v[176:179], v[80:95]
	v_mfma_f32_32x32x16_bf16 v[64:79], v[160:163], v[180:183], v[64:79]
	ds_read_b128 v[160:163], v184 offset:8192
	s_waitcnt lgkmcnt(0)
	v_mfma_f32_32x32x16_bf16 v[48:63], v[160:163], v[176:179], v[48:63]
	v_mfma_f32_32x32x16_bf16 v[32:47], v[160:163], v[180:183], v[32:47]
	ds_read_b128 v[160:163], v184 offset:12288
	s_waitcnt lgkmcnt(0)
	v_mfma_f32_32x32x16_bf16 v[16:31], v[160:163], v[176:179], v[16:31]
	v_add_u32_e32 v176, s8, v205
	v_add3_u32 v184, v176, v208, v164
	ds_read_b128 v[176:179], v184
	v_mfma_f32_32x32x16_bf16 v[0:15], v[160:163], v[180:183], v[0:15]
	v_add_u32_e32 v160, s29, v205
	v_add3_u32 v180, v160, v207, v164
	ds_read_b128 v[160:163], v180
	ds_read_b128 v[180:183], v180 offset:4096
	s_waitcnt lgkmcnt(1)
	v_mfma_f32_32x32x16_bf16 v[112:127], v[176:179], v[160:163], v[112:127]
	s_waitcnt lgkmcnt(0)
	v_mfma_f32_32x32x16_bf16 v[96:111], v[176:179], v[180:183], v[96:111]
	ds_read_b128 v[176:179], v184 offset:4096
	s_waitcnt lgkmcnt(0)
	v_mfma_f32_32x32x16_bf16 v[80:95], v[176:179], v[160:163], v[80:95]
	v_mfma_f32_32x32x16_bf16 v[64:79], v[176:179], v[180:183], v[64:79]
	ds_read_b128 v[176:179], v184 offset:8192
	s_waitcnt lgkmcnt(0)
	v_mfma_f32_32x32x16_bf16 v[48:63], v[176:179], v[160:163], v[48:63]
	v_mfma_f32_32x32x16_bf16 v[32:47], v[176:179], v[180:183], v[32:47]
	ds_read_b128 v[176:179], v184 offset:12288
	s_waitcnt lgkmcnt(0)
	v_mfma_f32_32x32x16_bf16 v[16:31], v[176:179], v[160:163], v[16:31]
	v_add_u32_e32 v160, s8, v204
	v_add3_u32 v184, v160, v208, v164
	ds_read_b128 v[160:163], v184
	v_mfma_f32_32x32x16_bf16 v[0:15], v[176:179], v[180:183], v[0:15]
	v_add_u32_e32 v176, s29, v204
	v_add3_u32 v180, v176, v207, v164
	ds_read_b128 v[176:179], v180
	ds_read_b128 v[180:183], v180 offset:4096
	s_waitcnt lgkmcnt(1)
	v_mfma_f32_32x32x16_bf16 v[112:127], v[160:163], v[176:179], v[112:127]
	s_waitcnt lgkmcnt(0)
	v_mfma_f32_32x32x16_bf16 v[96:111], v[160:163], v[180:183], v[96:111]
	ds_read_b128 v[160:163], v184 offset:4096
	s_waitcnt lgkmcnt(0)
	v_mfma_f32_32x32x16_bf16 v[80:95], v[160:163], v[176:179], v[80:95]
	v_mfma_f32_32x32x16_bf16 v[64:79], v[160:163], v[180:183], v[64:79]
	ds_read_b128 v[160:163], v184 offset:8192
	s_waitcnt lgkmcnt(0)
	v_mfma_f32_32x32x16_bf16 v[48:63], v[160:163], v[176:179], v[48:63]
	v_mfma_f32_32x32x16_bf16 v[32:47], v[160:163], v[180:183], v[32:47]
	ds_read_b128 v[160:163], v184 offset:12288
	s_waitcnt lgkmcnt(0)
	v_mfma_f32_32x32x16_bf16 v[16:31], v[160:163], v[176:179], v[16:31]
	v_add_u32_e32 v176, s8, v203
	v_add3_u32 v184, v176, v208, v164
	ds_read_b128 v[176:179], v184
	v_mfma_f32_32x32x16_bf16 v[0:15], v[160:163], v[180:183], v[0:15]
	v_add_u32_e32 v160, s29, v203
	v_add3_u32 v164, v160, v207, v164
	ds_read_b128 v[160:163], v164
	ds_read_b128 v[180:183], v164 offset:4096
	s_waitcnt lgkmcnt(1)
	v_mfma_f32_32x32x16_bf16 v[112:127], v[176:179], v[160:163], v[112:127]
	s_waitcnt lgkmcnt(0)
	v_mfma_f32_32x32x16_bf16 v[96:111], v[176:179], v[180:183], v[96:111]
	ds_read_b128 v[176:179], v184 offset:4096
	s_waitcnt lgkmcnt(0)
	v_mfma_f32_32x32x16_bf16 v[80:95], v[176:179], v[160:163], v[80:95]
	v_mfma_f32_32x32x16_bf16 v[64:79], v[176:179], v[180:183], v[64:79]
	ds_read_b128 v[176:179], v184 offset:8192
	s_waitcnt lgkmcnt(0)
	v_mfma_f32_32x32x16_bf16 v[48:63], v[176:179], v[160:163], v[48:63]
	v_mfma_f32_32x32x16_bf16 v[32:47], v[176:179], v[180:183], v[32:47]
	ds_read_b128 v[176:179], v184 offset:12288
	s_waitcnt lgkmcnt(0)
	s_barrier
	v_mfma_f32_32x32x16_bf16 v[16:31], v[176:179], v[160:163], v[16:31]
	v_mfma_f32_32x32x16_bf16 v[0:15], v[176:179], v[180:183], v[0:15]
	s_cbranch_vccz .LBB0_357
	s_lshl_b32 s8, s19, 2
	s_and_b32 s20, s8, 0xffffff00
	s_lshl_b32 s8, s19, 19
	s_and_b32 s8, s8, 0x1f80000
	s_add_u32 s70, s22, s8
	s_addc_u32 s71, s23, 0
	s_ashr_i32 s21, s20, 31
	s_lshl_b64 s[20:21], s[20:21], 11
	s_add_u32 s20, s2, s20
	s_addc_u32 s21, s3, s21
	v_lshl_add_u64 v[152:153], s[70:71], 0, v[174:175]
	v_lshl_add_u64 v[154:155], s[20:21], 0, v[174:175]
	v_lshlrev_b64 v[128:129], 1, v[172:173]
	v_lshlrev_b64 v[136:137], 1, v[170:171]
	v_lshlrev_b64 v[144:145], 1, v[168:169]
	v_lshlrev_b64 v[156:157], 1, v[166:167]
	v_lshl_add_u64 v[130:131], v[152:153], 0, v[128:129]
	v_lshl_add_u64 v[132:133], v[154:155], 0, v[128:129]
	v_lshl_add_u64 v[138:139], v[152:153], 0, v[136:137]
	v_lshl_add_u64 v[140:141], v[154:155], 0, v[136:137]
	v_lshl_add_u64 v[146:147], v[152:153], 0, v[144:145]
	v_lshl_add_u64 v[148:149], v[154:155], 0, v[144:145]
	v_lshl_add_u64 v[152:153], v[152:153], 0, v[156:157]
	v_lshl_add_u64 v[156:157], v[154:155], 0, v[156:157]
	global_load_dwordx4 v[128:131], v[130:131], off
	s_nop 0
	global_load_dwordx4 v[132:135], v[132:133], off
	s_nop 0
	global_load_dwordx4 v[136:139], v[138:139], off
	s_nop 0
	global_load_dwordx4 v[140:143], v[140:141], off
	s_nop 0
	global_load_dwordx4 v[144:147], v[146:147], off
	s_nop 0
	global_load_dwordx4 v[148:151], v[148:149], off
	s_nop 0
	global_load_dwordx4 v[152:155], v[152:153], off
	s_nop 0
	global_load_dwordx4 v[156:159], v[156:157], off

	.amdhsa_kernel _Z4megaILb1EEv6Params
		.amdhsa_group_segment_fixed_size 16
		.amdhsa_private_segment_fixed_size 0
		.amdhsa_kernarg_size 472
		.amdhsa_user_sgpr_count 2
		.amdhsa_user_sgpr_dispatch_ptr 0
		.amdhsa_user_sgpr_queue_ptr 0
		.amdhsa_user_sgpr_kernarg_segment_ptr 1
		.amdhsa_user_sgpr_dispatch_id 0
		.amdhsa_user_sgpr_kernarg_preload_length 0
		.amdhsa_user_sgpr_kernarg_preload_offset 0
		.amdhsa_user_sgpr_private_segment_size 0
		.amdhsa_uses_dynamic_stack 0
		.amdhsa_enable_private_segment 0
		.amdhsa_system_sgpr_workgroup_id_x 1
		.amdhsa_system_sgpr_workgroup_id_y 0
		.amdhsa_system_sgpr_workgroup_id_z 0
		.amdhsa_system_sgpr_workgroup_info 0
		.amdhsa_system_vgpr_workitem_id 2
		.amdhsa_next_free_vgpr 256
		.amdhsa_next_free_sgpr 102
		.amdhsa_accum_offset 256
		.amdhsa_reserve_vcc 1
		.amdhsa_float_round_mode_32 0
		.amdhsa_float_round_mode_16_64 0
		.amdhsa_float_denorm_mode_32 3
		.amdhsa_float_denorm_mode_16_64 3
		.amdhsa_dx10_clamp 1
		.amdhsa_ieee_mode 1
		.amdhsa_fp16_overflow 0
		.amdhsa_tg_split 0
		.amdhsa_exception_fp_ieee_invalid_op 0
		.amdhsa_exception_fp_denorm_src 0
		.amdhsa_exception_fp_ieee_div_zero 0
		.amdhsa_exception_fp_ieee_overflow 0
		.amdhsa_exception_fp_ieee_underflow 0
		.amdhsa_exception_fp_ieee_inexact 0
		.amdhsa_exception_int_div_zero 0
	.end_amdhsa_kernel

amdhsa.kernels:
  - .agpr_count:     0
    .args:
      - .offset:         0
        .size:           216
        .value_kind:     by_value
      - .offset:         216
        .size:           4
        .value_kind:     hidden_block_count_x
      - .offset:         220
        .size:           4
        .value_kind:     hidden_block_count_y
      - .offset:         224
        .size:           4
        .value_kind:     hidden_block_count_z
      - .offset:         228
        .size:           2
        .value_kind:     hidden_group_size_x
      - .offset:         230
        .size:           2
        .value_kind:     hidden_group_size_y
      - .offset:         232
        .size:           2
        .value_kind:     hidden_group_size_z
      - .offset:         234
        .size:           2
        .value_kind:     hidden_remainder_x
      - .offset:         236
        .size:           2
        .value_kind:     hidden_remainder_y
      - .offset:         238
        .size:           2
        .value_kind:     hidden_remainder_z
      - .offset:         256
        .size:           8
        .value_kind:     hidden_global_offset_x
      - .offset:         264
        .size:           8
        .value_kind:     hidden_global_offset_y
      - .offset:         272
        .size:           8
        .value_kind:     hidden_global_offset_z
      - .offset:         280
        .size:           2
        .value_kind:     hidden_grid_dims
      - .offset:         304
        .size:           8
        .value_kind:     hidden_multigrid_sync_arg
      - .offset:         336
        .size:           4
        .value_kind:     hidden_dynamic_lds_size
    .group_segment_fixed_size: 16
    .kernarg_segment_align: 8
    .kernarg_segment_size: 472
    .language:       OpenCL C
    .language_version:
      - 2
      - 0
    .max_flat_workgroup_size: 512
    .name:           _Z4megaILb1EEv6Params
    .private_segment_fixed_size: 0
    .sgpr_count:     108
    .sgpr_spill_count: 75
    .symbol:         _Z4megaILb1EEv6Params.kd
    .uniform_work_group_size: 1
    .uses_dynamic_stack: false
    .vgpr_count:     256
    .vgpr_spill_count: 0
    .wavefront_size: 64
